# scan loop: one static s_setprio 1 for waves 4-7 (the younger half of each SIMD pair), reset at loop exit
# speedup vs baseline: 1.0361x; 1.0030x over previous
; #define LDS_BARRIER() do { asm volatile("s_waitcnt lgkmcnt(0)" ::: "memory"); __builtin_amdgcn_s_barrier(); asm volatile("" ::: "memory"); } while (0)
; __device__ __forceinline__ void scan_unit(LAS unsigned char* lds, int uidx, const bf16* Qg, const bf16* Kg, bf16* Vg, const bf16* KT, const bf16* QK, const float* GC, float* SSQ, float* sp_gdn) {
;     ...
;     float* so = sp_gdn + ((size_t)(b * 8 + h) * 128 + 16 * s + 4 * lq) * 128 + slab * 32 + li;
; #pragma unroll
;     for (int r = 0; r < 4; ++r) { so[(size_t)r * 128] = S0[r]; so[(size_t)r * 128 + 16] = S1[r]; }
;     LDS_BARRIER();
.Lscan_store:
	s_setprio 0
	s_ashr_i32 s7, s6, 31
	s_lshl_b64 s[0:1], s[6:7], 7
	s_add_u32 s0, s0, s35
	s_addc_u32 s1, s1, 0
	v_mov_b32_e32 v9, s1
	v_or_b32_e32 v8, s0, v70
	v_lshlrev_b64 v[8:9], 9, v[8:9]
	v_lshl_add_u64 v[8:9], s[14:15], 0, v[8:9]
	s_lshl_b32 s8, s37, 2
	v_lshl_add_u64 v[8:9], v[8:9], 0, s[8:9]
	v_lshlrev_b32_e32 v68, 2, v156
	v_lshl_add_u64 v[8:9], v[8:9], 0, v[68:69]
	v_lshl_add_u64 v[10:11], v[8:9], 0, s[12:13]
	v_add_co_u32_e64 v8, s[6:7], s3, v8
	s_add_i32 s36, s36, s88
	s_nop 0
	v_addc_co_u32_e64 v9, s[6:7], 0, v9, s[6:7]
	global_store_dword v[8:9], v4, off
	global_store_dword v[10:11], v0, off offset:64
	global_store_dword v[10:11], v5, off offset:512
	global_store_dword v[10:11], v1, off offset:576
	global_store_dword v[10:11], v6, off offset:1024
	global_store_dword v[10:11], v2, off offset:1088
	global_store_dword v[10:11], v7, off offset:1536
	global_store_dword v[10:11], v3, off offset:1600
	s_waitcnt lgkmcnt(0)
	s_barrier
	s_cmpk_gt_i32 s36, 0xff
	s_cbranch_scc1 .LBB0_851

; __device__ __forceinline__ void scan_unit(LAS unsigned char* lds, int uidx, const bf16* Qg, const bf16* Kg, bf16* Vg, const bf16* KT, const bf16* QK, const float* GC, float* SSQ, float* sp_gdn) {
;     ...
;     ScanFrag cur, nxt;
;     scan_load(cur, 0, b, h, ti, s, li, lq, ucol, Qg, Kg, Vg, KT, QK, GC);
;     for (int n = 0; n < 32; ++n) {
;         const int m0 = b * 2048 + n * 64, rowb = m0 + 16 * ti + 4 * lq;
;         __builtin_amdgcn_sched_barrier(0);
.Lscan_sl3g:
	s_cmp_lt_u32 s95, 4
	s_cbranch_scc1 .Lscan_prio
	s_setprio 1
